# GEMM1 fp8 K-loop: next-unit A-panel readiness counter loaded one iteration early (non-blocking); the blocking poll at the unit boundary only runs if that early value was not yet ready
# baseline (speedup 1.0000x reference)
; template <class Epi, class Sched, bool ALIGN_EPI = false, bool SP2 = false, bool F8 = false>
; __device__ __forceinline__ void gemm_phase(PG8_LAS unsigned char* lds, const Gemm g, const Sched& S, const Epi& E) {
;     ...
;         const bool has_next = S.next(ui + 1, nxt);
;         const char* nA = has_next ? (const char*)g.A + (size_t)nxt.pm * tstep + (size_t)nxt.kt0 * kstep : cA; const char* nB = has_next ? (const char*)g.Bt + (size_t)nxt.pn * tstep + (size_t)nxt.kt0 * kstep : cB;
;         const int nt = cur.nkt;
;         for (int t = 0; t < nt; t += 2) {
;             const bool last = (t == nt - 2);
;             const char* a1 = cA + (size_t)(t + 1) * kstep;
;             const char* a2 = last ? nA : cA + (size_t)(t + 2) * kstep; const char* b2 = last ? nB : cB + (size_t)(t + 2) * kstep;
;             const char* a3 = a2 + kstep; const char* b3 = b2 + kstep;
;             if (last && has_next) S.a_ready(nxt);
;     ...
; #pragma unroll
;         for (int a = 0; a < 2; ++a)
; #pragma unroll
;             for (int b = 0; b < 2; ++b)
; #pragma unroll
;                 for (int m = 0; m < 4; ++m)
; #pragma unroll
;                     for (int n = 0; n < 2; ++n) acc[a][b][m][n] = (f32x4){0.f, 0.f, 0.f, 0.f};
.LBB0_649:
	s_ashr_i32 s69, s68, 31
	s_lshl_b64 s[70:71], s[68:69], 19
	s_add_u32 s33, s26, s70
	s_addc_u32 s34, s27, s71
	s_and_b64 s[70:71], s[8:9], exec
	s_cselect_b32 s71, s34, s5
	s_cselect_b32 s70, s33, s4
	s_ashr_i32 s67, s66, 31
	s_lshl_b64 s[72:73], s[66:67], 19
	s_add_u32 s33, s47, s72
	s_addc_u32 s34, s96, s73
	s_and_b64 s[72:73], s[8:9], exec
	s_cselect_b32 s73, s34, s7
	s_cselect_b32 s72, s33, s6
	s_add_u32 s67, s4, 0x40000
	s_addc_u32 s69, s5, 0
	s_lshl_b32 s78, s68, 6
	s_add_i32 s45, s48, -2
	s_ashr_i32 s79, s78, 31
	s_cmp_gt_i32 s68, -1
	s_cselect_b64 s[76:77], -1, 0
	s_and_b64 s[76:77], s[58:59], s[76:77]
	s_cmp_lt_u32 s68, 16
	s_cselect_b32 s33, 8, 36
	s_lshl_b64 s[78:79], s[78:79], 2
	s_getpc_b64 s[84:85]
	s_add_u32 s84, s84, g_ctl@rel32@lo+40964
	s_addc_u32 s85, s85, g_ctl@rel32@hi+40972
	s_add_u32 s78, s84, s78
	v_mov_b32_e32 v34, 0
	v_mov_b32_e32 v250, 0
	s_addc_u32 s79, s85, s79
	s_mov_b32 s46, 0
	v_mov_b32_e32 v35, v34
	v_mov_b32_e32 v36, v34
	v_mov_b32_e32 v37, v34
	v_mov_b32_e32 v38, v34
	v_mov_b32_e32 v39, v34
	v_mov_b32_e32 v40, v34
	v_mov_b32_e32 v41, v34
	v_mov_b32_e32 v50, v34
	v_mov_b32_e32 v51, v34
	v_mov_b32_e32 v52, v34
	v_mov_b32_e32 v53, v34
	v_mov_b32_e32 v54, v34
	v_mov_b32_e32 v55, v34
	v_mov_b32_e32 v56, v34
	v_mov_b32_e32 v57, v34
	v_mov_b32_e32 v66, v34
	v_mov_b32_e32 v67, v34
	v_mov_b32_e32 v68, v34
	v_mov_b32_e32 v69, v34
	v_mov_b32_e32 v70, v34
	v_mov_b32_e32 v71, v34
	v_mov_b32_e32 v72, v34
	v_mov_b32_e32 v73, v34
	v_mov_b32_e32 v82, v34
	v_mov_b32_e32 v83, v34
	v_mov_b32_e32 v84, v34
	v_mov_b32_e32 v85, v34
	v_mov_b32_e32 v86, v34
	v_mov_b32_e32 v87, v34
	v_mov_b32_e32 v88, v34
	v_mov_b32_e32 v89, v34
	v_mov_b32_e32 v42, v34
	v_mov_b32_e32 v43, v34
	v_mov_b32_e32 v44, v34
	v_mov_b32_e32 v45, v34
	v_mov_b32_e32 v46, v34
	v_mov_b32_e32 v47, v34
	v_mov_b32_e32 v48, v34
	v_mov_b32_e32 v49, v34
	v_mov_b32_e32 v58, v34
	v_mov_b32_e32 v59, v34
	v_mov_b32_e32 v60, v34
	v_mov_b32_e32 v61, v34
	v_mov_b32_e32 v62, v34
	v_mov_b32_e32 v63, v34
	v_mov_b32_e32 v64, v34
	v_mov_b32_e32 v65, v34
	v_mov_b32_e32 v74, v34
	v_mov_b32_e32 v75, v34
	v_mov_b32_e32 v76, v34
	v_mov_b32_e32 v77, v34
	v_mov_b32_e32 v78, v34
	v_mov_b32_e32 v79, v34
	v_mov_b32_e32 v80, v34
	v_mov_b32_e32 v81, v34
	v_mov_b32_e32 v90, v34
	v_mov_b32_e32 v91, v34
	v_mov_b32_e32 v92, v34
	v_mov_b32_e32 v93, v34
	v_mov_b32_e32 v94, v34
	v_mov_b32_e32 v95, v34
	v_mov_b32_e32 v96, v34
	v_mov_b32_e32 v97, v34
	v_mov_b32_e32 v98, v34
	v_mov_b32_e32 v99, v34
	v_mov_b32_e32 v100, v34
	v_mov_b32_e32 v101, v34
	v_mov_b32_e32 v102, v34
	v_mov_b32_e32 v103, v34
	v_mov_b32_e32 v104, v34
	v_mov_b32_e32 v105, v34
	v_mov_b32_e32 v114, v34
	v_mov_b32_e32 v115, v34
	v_mov_b32_e32 v116, v34
	v_mov_b32_e32 v117, v34
	v_mov_b32_e32 v118, v34
	v_mov_b32_e32 v119, v34
	v_mov_b32_e32 v120, v34
	v_mov_b32_e32 v121, v34
	v_mov_b32_e32 v130, v34
	v_mov_b32_e32 v131, v34
	v_mov_b32_e32 v132, v34
	v_mov_b32_e32 v133, v34
	v_mov_b32_e32 v134, v34
	v_mov_b32_e32 v135, v34
	v_mov_b32_e32 v136, v34
	v_mov_b32_e32 v137, v34
	v_mov_b32_e32 v146, v34
	v_mov_b32_e32 v147, v34
	v_mov_b32_e32 v148, v34
	v_mov_b32_e32 v149, v34
	v_mov_b32_e32 v150, v34
	v_mov_b32_e32 v151, v34
	v_mov_b32_e32 v152, v34
	v_mov_b32_e32 v153, v34
	v_mov_b32_e32 v106, v34
	v_mov_b32_e32 v107, v34
	v_mov_b32_e32 v108, v34
	v_mov_b32_e32 v109, v34
	v_mov_b32_e32 v110, v34
	v_mov_b32_e32 v111, v34
	v_mov_b32_e32 v112, v34
	v_mov_b32_e32 v113, v34
	v_mov_b32_e32 v122, v34
	v_mov_b32_e32 v123, v34
	v_mov_b32_e32 v124, v34
	v_mov_b32_e32 v125, v34
	v_mov_b32_e32 v126, v34
	v_mov_b32_e32 v127, v34
	v_mov_b32_e32 v128, v34
	v_mov_b32_e32 v129, v34
	v_mov_b32_e32 v138, v34
	v_mov_b32_e32 v139, v34
	v_mov_b32_e32 v140, v34
	v_mov_b32_e32 v141, v34
	v_mov_b32_e32 v142, v34
	v_mov_b32_e32 v143, v34
	v_mov_b32_e32 v144, v34
	v_mov_b32_e32 v145, v34
	v_mov_b32_e32 v154, v34
	v_mov_b32_e32 v155, v34
	v_mov_b32_e32 v156, v34
	v_mov_b32_e32 v157, v34
	v_mov_b32_e32 v158, v34
	v_mov_b32_e32 v159, v34
	v_mov_b32_e32 v160, v34
	v_mov_b32_e32 v161, v34
	s_branch .LBB0_653

;     __device__ __forceinline__ void a_ready(const Unit& u) const {
;         if (threadIdx.x < 64 && u.pm >= first) { unsigned sp = 0; const unsigned nd = (u.pm < split) ? need_lo : need;
;             while ((unsigned)__builtin_amdgcn_readfirstlane(__hip_atomic_load(ready + 64 * u.pm, __ATOMIC_RELAXED, __HIP_MEMORY_SCOPE_AGENT)) < nd) { __builtin_amdgcn_s_sleep(2); if (++sp > (1u << 22)) break; }
;             asm volatile("" ::: "memory");
;             asm volatile("s_waitcnt vmcnt(0)" ::: "memory"); }
;         asm volatile("" ::: "memory"); __builtin_amdgcn_s_barrier(); asm volatile("" ::: "memory");
; template <class Epi, class Sched, bool ALIGN_EPI = false, bool SP2 = false, bool F8 = false>
; __device__ __forceinline__ void gemm_phase(PG8_LAS unsigned char* lds, const Gemm g, const Sched& S, const Epi& E) {
;     ...
;         for (int t = 0; t < nt; t += 2) {
;             const bool last = (t == nt - 2);
;             const char* a1 = cA + (size_t)(t + 1) * kstep;
;             const char* a2 = last ? nA : cA + (size_t)(t + 2) * kstep; const char* b2 = last ? nB : cB + (size_t)(t + 2) * kstep;
;             const char* a3 = a2 + kstep; const char* b3 = b2 + kstep;
;             if (last && has_next) S.a_ready(nxt);
.LBB0_653:
	s_add_i32 s88, s45, -2
	s_cmp_eq_u32 s46, s88
	s_cbranch_scc0 .Lpoll_early_skip
	s_and_b64 vcc, exec, s[8:9]
	s_cbranch_vccz .Lpoll_early_skip
	global_load_dword v250, v173, s[78:79] sc1
.Lpoll_early_skip:
	s_cmp_eq_u32 s46, s45
	s_cselect_b64 s[84:85], -1, 0
	s_and_b64 s[86:87], s[8:9], s[84:85]
	s_andn2_b64 vcc, exec, s[86:87]
	s_cbranch_vccnz .LBB0_652
	s_and_saveexec_b64 s[86:87], s[76:77]
	s_cbranch_execz .LBB0_651
	v_readfirstlane_b32 s88, v250
	s_cmp_ge_u32 s88, s33
	s_cbranch_scc1 .LBB0_651
	s_mov_b32 s34, 0x400001
	s_branch .LBB0_657
